# pre-issued barrier poll + L1 invalidate in the middle of the two R4 filler bodies (wave 0), spin loop only as fallback
# speedup vs baseline: 1.0019x; 1.0019x over previous
.Llb865_arrdone:
	s_mov_b64 exec, s[8:9]
	v_writelane_b32 v255, s0, 40
	v_writelane_b32 v255, s1, 41
	v_writelane_b32 v255, s2, 42
	v_writelane_b32 v255, s3, 43
	v_writelane_b32 v255, s6, 44
	v_writelane_b32 v255, s7, 45
	v_writelane_b32 v255, s25, 46
	v_writelane_b32 v255, s26, 47
	v_writelane_b32 v255, s27, 48
	v_writelane_b32 v255, s28, 49
	v_writelane_b32 v255, s49, 50
	v_mov_b32_e32 v222, v1
	v_mov_b32_e32 v223, v138
	v_mov_b32_e32 v224, v139
	v_mov_b32_e32 v225, v140
	v_mov_b32_e32 v226, v141
	v_mov_b32_e32 v227, v142
	v_mov_b32_e32 v228, v143
	v_mov_b32_e32 v229, v144
	v_mov_b32_e32 v230, v145
	v_mov_b32_e32 v231, v154
	v_mov_b32_e32 v232, v155
	v_mov_b32_e32 v233, v156
	v_mov_b32_e32 v234, v157
	v_mov_b32_e32 v235, v158
	v_mov_b32_e32 v236, v159
	v_mov_b32_e32 v237, v160
	s_add_u32 s22, s62, 0x40d000
	s_addc_u32 s23, s63, 0
	v_mov_b32_e32 v239, 0x400
	v_mov_b32_e32 v238, 0
	s_movk_i32 s9, 0x2000
	v_mbcnt_lo_u32_b32 v1, -1, 0
	v_mbcnt_hi_u32_b32 v3, -1, v1
	v_and_b32_e32 v1, 64, v3
	v_add_u32_e32 v4, 64, v1
	v_xor_b32_e32 v1, 1, v3
	v_cmp_lt_i32_e32 vcc, v1, v4
	v_xor_b32_e32 v6, 2, v3
	s_lshl_b32 s2, s44, 1
	v_cndmask_b32_e32 v1, v3, v1, vcc
	v_cmp_lt_i32_e32 vcc, v6, v4
	v_lshlrev_b32_e32 v2, 3, v191
	v_mov_b32_e32 v5, 0
	v_cndmask_b32_e32 v6, v3, v6, vcc
	v_lshlrev_b32_e32 v61, 2, v6
	v_xor_b32_e32 v6, 4, v3
	v_cmp_lt_i32_e32 vcc, v6, v4
	v_or_b32_e32 v8, 0x400, v2
	s_ashr_i32 s3, s2, 31
	v_cndmask_b32_e32 v6, v3, v6, vcc
	v_lshlrev_b32_e32 v75, 2, v6
	v_xor_b32_e32 v6, 8, v3
	v_cmp_lt_i32_e32 vcc, v6, v4
	v_or_b32_e32 v10, 0x600, v2
	v_lshlrev_b32_e32 v12, 2, v8
	v_cndmask_b32_e32 v6, v3, v6, vcc
	v_mov_b32_e32 v13, v5
	s_lshl_b64 s[0:1], s[2:3], 12
	v_lshlrev_b32_e32 v77, 2, v6
	v_xor_b32_e32 v6, 16, v3
	v_lshl_add_u64 v[52:53], s[58:59], 0, v[12:13]
	v_lshlrev_b32_e32 v12, 2, v10
	s_add_u32 s0, s62, s0
	v_cmp_lt_i32_e32 vcc, v6, v4
	v_lshl_add_u64 v[54:55], s[58:59], 0, v[12:13]
	v_lshlrev_b32_e32 v12, 4, v191
	s_addc_u32 s1, s63, s1
	v_cndmask_b32_e32 v6, v3, v6, vcc
	v_lshl_add_u64 v[12:13], s[0:1], 0, v[12:13]
	s_mov_b64 s[0:1], 0x10800000
	s_ashr_i32 s49, s48, 31
	v_lshlrev_b32_e32 v94, 2, v6
	v_xor_b32_e32 v6, 32, v3
	v_lshl_add_u64 v[56:57], v[12:13], 0, s[0:1]
	s_lshl_b64 s[4:5], s[48:49], 12
	s_lshl_b64 s[0:1], s[2:3], 13
	v_cmp_lt_i32_e32 vcc, v6, v4
	s_add_u32 s0, s60, s0
	v_lshlrev_b32_e32 v4, 5, v191
	v_cndmask_b32_e32 v3, v3, v6, vcc
	v_or_b32_e32 v6, 0x200, v2
	s_addc_u32 s1, s61, s1
	v_lshlrev_b32_e32 v1, 2, v1
	v_lshlrev_b32_e32 v95, 2, v3
	v_lshl_add_u64 v[50:51], s[58:59], 0, v[4:5]
	v_lshl_add_u64 v[58:59], s[0:1], 0, v[4:5]
	s_lshl_b64 s[6:7], s[48:49], 13
	s_movk_i32 s3, 0x1000
	s_mov_b32 s12, 0x4001000
	v_lshlrev_b32_e32 v96, 2, v2
	v_lshlrev_b32_e32 v97, 2, v6
	v_lshlrev_b32_e32 v98, 2, v8
	v_lshlrev_b32_e32 v99, 2, v10
	s_mov_b32 s8, 0x3a000000
	s_mov_b32 s13, 0x800000
	s_movk_i32 s14, 0x3000
	v_mov_b32_e32 v60, 0x358637bd
	v_add_co_u32_e32 v30, vcc, 0x4000000, v56
	global_load_dwordx4 v[22:25], v[56:57], off
	global_load_dwordx4 v[18:21], v[56:57], off offset:1024
	global_load_dwordx4 v[14:17], v[56:57], off offset:2048
	global_load_dwordx4 v[10:13], v[56:57], off offset:3072
	v_addc_co_u32_e32 v31, vcc, 0, v57, vcc
	v_add_co_u32_e32 v32, vcc, s3, v56
	global_load_dwordx4 v[2:5], v[50:51], off offset:16
	global_load_dwordx4 v[6:9], v[50:51], off
	v_addc_co_u32_e32 v33, vcc, 0, v57, vcc
	global_load_dwordx4 v[78:81], v[30:31], off
	global_load_dwordx4 v[42:45], v[30:31], off offset:1024
	global_load_dwordx4 v[34:37], v[30:31], off offset:2048
	global_load_dwordx4 v[26:29], v[30:31], off offset:3072
	global_load_dwordx4 v[82:85], v[32:33], off
	global_load_dwordx4 v[100:103], v[32:33], off offset:1024
	global_load_dwordx4 v[104:107], v[32:33], off offset:2048
	global_load_dwordx4 v[108:111], v[32:33], off offset:3072
	v_add_co_u32_e32 v66, vcc, s12, v56
	v_add_co_u32_e64 v64, s[0:1], s9, v58
	s_nop 0
	v_addc_co_u32_e32 v67, vcc, 0, v57, vcc
	global_load_dwordx4 v[112:115], v[66:67], off
	global_load_dwordx4 v[46:49], v[66:67], off offset:1024
	global_load_dwordx4 v[38:41], v[66:67], off offset:2048
	global_load_dwordx4 v[30:33], v[66:67], off offset:3072
	v_addc_co_u32_e64 v65, s[0:1], 0, v59, s[0:1]
	v_add_co_u32_e64 v62, s[0:1], s14, v58
	s_add_i32 s10, s2, 0xffffe000
	s_nop 0
	v_addc_co_u32_e64 v63, s[0:1], 0, v59, s[0:1]
	s_lshr_b32 s0, s10, 10
	s_add_i32 s0, s0, 1
	s_cmpk_gt_i32 s2, 0x1fff
	s_cselect_b32 s0, s0, 0
	s_mul_hi_u32 s1, s0, 0xc000
	s_mul_i32 s0, s0, 0xc000
	s_add_u32 s0, s62, s0
	s_addc_u32 s1, s63, s1
	s_add_u32 s10, s0, 0xa000
	s_addc_u32 s11, s1, 0
	global_load_dwordx4 v[116:119], v96, s[10:11] offset:16
	global_load_dwordx4 v[120:123], v96, s[10:11]
	s_add_i32 s2, s2, s48
	v_lshl_add_u64 v[56:57], v[56:57], 0, s[4:5]
	s_cmpk_lt_i32 s2, 0x4000
	s_waitcnt vmcnt(0)
	v_and_b32_e32 v125, 0xffff0000, v22
	v_lshlrev_b32_e32 v124, 16, v22
	v_lshlrev_b32_e32 v126, 16, v23
	v_and_b32_e32 v127, 0xffff0000, v23
	v_lshlrev_b32_e32 v70, 16, v16
	v_and_b32_e32 v71, 0xffff0000, v16
	v_lshlrev_b32_e32 v72, 16, v17
	v_and_b32_e32 v73, 0xffff0000, v17
	v_lshlrev_b32_e32 v16, 16, v12
	v_and_b32_e32 v207, 0xffff0000, v82
	v_and_b32_e32 v17, 0xffff0000, v12
	v_mov_b32_e32 v137, v125
	v_lshlrev_b32_e32 v206, 16, v82
	v_lshlrev_b32_e32 v22, 16, v110
	v_and_b32_e32 v23, 0xffff0000, v110
	v_mov_b32_e32 v136, v207
	v_lshlrev_b32_e32 v86, 16, v18
	v_and_b32_e32 v87, 0xffff0000, v18
	v_lshlrev_b32_e32 v88, 16, v19
	v_and_b32_e32 v89, 0xffff0000, v19
	v_lshlrev_b32_e32 v90, 16, v20
	v_and_b32_e32 v91, 0xffff0000, v20
	v_lshlrev_b32_e32 v92, 16, v21
	v_and_b32_e32 v93, 0xffff0000, v21
	v_mov_b32_e32 v135, v124
	v_pk_mul_f32 v[170:171], v[16:17], v[16:17]
	v_lshlrev_b32_e32 v208, 16, v83
	v_lshlrev_b32_e32 v214, 16, v100
	v_and_b32_e32 v215, 0xffff0000, v100
	v_lshlrev_b32_e32 v216, 16, v101
	v_and_b32_e32 v217, 0xffff0000, v101
	v_lshlrev_b32_e32 v218, 16, v102
	v_and_b32_e32 v219, 0xffff0000, v102
	v_lshlrev_b32_e32 v220, 16, v103
	v_and_b32_e32 v221, 0xffff0000, v103
	v_lshlrev_b32_e32 v18, 16, v108
	v_and_b32_e32 v19, 0xffff0000, v108
	v_lshlrev_b32_e32 v20, 16, v109
	v_and_b32_e32 v21, 0xffff0000, v109
	v_lshlrev_b32_e32 v100, 16, v112
	v_and_b32_e32 v101, 0xffff0000, v112
	v_lshlrev_b32_e32 v102, 16, v113
	v_and_b32_e32 v103, 0xffff0000, v113
	v_mov_b32_e32 v134, v206
	v_pk_mul_f32 v[108:109], v[22:23], v[22:23]
	v_pk_mul_f32 v[112:113], v[136:137], v[136:137]
	v_mov_b32_e32 v139, v126
	v_mov_b32_e32 v203, v170
	v_and_b32_e32 v209, 0xffff0000, v83
	v_mov_b32_e32 v138, v208
	v_mov_b32_e32 v202, v108
	v_mov_b32_e32 v170, v109
	v_pk_fma_f32 v[108:109], v[134:135], v[134:135], v[112:113]
	v_lshlrev_b32_e32 v128, 16, v24
	v_mov_b32_e32 v141, v127
	v_lshlrev_b32_e32 v210, 16, v84
	v_mov_b32_e32 v140, v209
	v_pk_fma_f32 v[108:109], v[138:139], v[138:139], v[108:109]
	v_and_b32_e32 v129, 0xffff0000, v24
	v_mov_b32_e32 v143, v128
	v_and_b32_e32 v211, 0xffff0000, v84
	v_mov_b32_e32 v142, v210
	v_pk_fma_f32 v[108:109], v[140:141], v[140:141], v[108:109]
	v_lshlrev_b32_e32 v130, 16, v25
	v_mov_b32_e32 v145, v129
	v_lshlrev_b32_e32 v212, 16, v85
	v_mov_b32_e32 v144, v211
	v_pk_fma_f32 v[108:109], v[142:143], v[142:143], v[108:109]
	v_and_b32_e32 v131, 0xffff0000, v25
	v_mov_b32_e32 v147, v130
	v_and_b32_e32 v213, 0xffff0000, v85
	v_mov_b32_e32 v146, v212
	v_pk_fma_f32 v[108:109], v[144:145], v[144:145], v[108:109]
	v_mov_b32_e32 v133, v131
	v_mov_b32_e32 v132, v213
	v_pk_fma_f32 v[108:109], v[146:147], v[146:147], v[108:109]
	v_mov_b32_e32 v149, v86
	v_mov_b32_e32 v148, v214
	v_pk_fma_f32 v[108:109], v[132:133], v[132:133], v[108:109]
	v_mov_b32_e32 v151, v87
	v_mov_b32_e32 v150, v215
	v_pk_fma_f32 v[108:109], v[148:149], v[148:149], v[108:109]
	v_mov_b32_e32 v153, v88
	v_mov_b32_e32 v152, v216
	v_pk_fma_f32 v[108:109], v[150:151], v[150:151], v[108:109]
	v_mov_b32_e32 v155, v89
	v_mov_b32_e32 v154, v217
	v_pk_fma_f32 v[108:109], v[152:153], v[152:153], v[108:109]
	v_mov_b32_e32 v157, v90
	v_mov_b32_e32 v156, v218
	v_pk_fma_f32 v[108:109], v[154:155], v[154:155], v[108:109]
	v_mov_b32_e32 v159, v91
	v_mov_b32_e32 v158, v219
	v_pk_fma_f32 v[108:109], v[156:157], v[156:157], v[108:109]
	v_mov_b32_e32 v161, v92
	v_mov_b32_e32 v160, v220
	v_pk_fma_f32 v[108:109], v[158:159], v[158:159], v[108:109]
	v_lshlrev_b32_e32 v66, 16, v14
	v_mov_b32_e32 v163, v93
	v_lshlrev_b32_e32 v194, 16, v78
	v_and_b32_e32 v195, 0xffff0000, v78
	v_lshlrev_b32_e32 v78, 16, v104
	v_mov_b32_e32 v162, v221
	v_pk_fma_f32 v[108:109], v[160:161], v[160:161], v[108:109]
	v_and_b32_e32 v67, 0xffff0000, v14
	v_mov_b32_e32 v165, v66
	v_lshlrev_b32_e32 v196, 16, v79
	v_and_b32_e32 v197, 0xffff0000, v79
	v_and_b32_e32 v79, 0xffff0000, v104
	v_mov_b32_e32 v164, v78
	v_pk_fma_f32 v[108:109], v[162:163], v[162:163], v[108:109]
	v_lshlrev_b32_e32 v68, 16, v15
	v_mov_b32_e32 v167, v67
	v_lshlrev_b32_e32 v198, 16, v80
	v_and_b32_e32 v199, 0xffff0000, v80
	v_lshlrev_b32_e32 v80, 16, v105
	v_mov_b32_e32 v166, v79
	v_pk_fma_f32 v[108:109], v[164:165], v[164:165], v[108:109]
	v_and_b32_e32 v69, 0xffff0000, v15
	v_mov_b32_e32 v169, v68
	v_lshlrev_b32_e32 v200, 16, v81
	v_and_b32_e32 v201, 0xffff0000, v81
	v_and_b32_e32 v81, 0xffff0000, v105
	v_mov_b32_e32 v168, v80
	v_pk_fma_f32 v[108:109], v[166:167], v[166:167], v[108:109]
	v_mov_b32_e32 v175, v69
	v_lshlrev_b32_e32 v82, 16, v106
	v_mov_b32_e32 v174, v81
	v_pk_fma_f32 v[108:109], v[168:169], v[168:169], v[108:109]
	v_mov_b32_e32 v177, v70
	v_and_b32_e32 v83, 0xffff0000, v106
	v_mov_b32_e32 v176, v82
	v_pk_fma_f32 v[108:109], v[174:175], v[174:175], v[108:109]
	v_mov_b32_e32 v179, v71
	v_lshlrev_b32_e32 v84, 16, v107
	v_mov_b32_e32 v178, v83
	v_pk_fma_f32 v[108:109], v[176:177], v[176:177], v[108:109]
	v_mov_b32_e32 v181, v72
	v_and_b32_e32 v85, 0xffff0000, v107
	v_mov_b32_e32 v180, v84
	v_pk_fma_f32 v[108:109], v[178:179], v[178:179], v[108:109]
	v_lshlrev_b32_e32 v14, 16, v10
	v_mov_b32_e32 v183, v73
	v_mov_b32_e32 v182, v85
	v_pk_fma_f32 v[108:109], v[180:181], v[180:181], v[108:109]
	v_and_b32_e32 v15, 0xffff0000, v10
	v_mov_b32_e32 v185, v14
	v_mov_b32_e32 v184, v18
	v_pk_fma_f32 v[108:109], v[182:183], v[182:183], v[108:109]
	v_lshlrev_b32_e32 v10, 16, v11
	v_mov_b32_e32 v187, v15
	v_mov_b32_e32 v186, v19
	v_pk_fma_f32 v[108:109], v[184:185], v[184:185], v[108:109]
	v_and_b32_e32 v11, 0xffff0000, v11
	v_mov_b32_e32 v189, v10
	v_mov_b32_e32 v188, v20
	v_pk_fma_f32 v[108:109], v[186:187], v[186:187], v[108:109]
	v_mov_b32_e32 v193, v11
	v_mov_b32_e32 v192, v21
	v_pk_fma_f32 v[108:109], v[188:189], v[188:189], v[108:109]
	v_lshlrev_b32_e32 v12, 16, v13
	v_and_b32_e32 v13, 0xffff0000, v13
	v_lshlrev_b32_e32 v24, 16, v111
	v_and_b32_e32 v25, 0xffff0000, v111
	v_pk_fma_f32 v[108:109], v[192:193], v[192:193], v[108:109]
	v_pk_mul_f32 v[172:173], v[12:13], v[12:13]
	v_pk_mul_f32 v[110:111], v[24:25], v[24:25]
	v_pk_add_f32 v[108:109], v[202:203], v[108:109]
	v_mov_b32_e32 v205, v172
	v_mov_b32_e32 v204, v110
	v_pk_add_f32 v[108:109], v[170:171], v[108:109]
	v_mov_b32_e32 v172, v111
	v_pk_add_f32 v[108:109], v[204:205], v[108:109]
	v_lshlrev_b32_e32 v104, 16, v114
	v_pk_add_f32 v[108:109], v[172:173], v[108:109]
	ds_bpermute_b32 v111, v1, v109
	ds_bpermute_b32 v110, v1, v108
	v_and_b32_e32 v105, 0xffff0000, v114
	v_lshlrev_b32_e32 v106, 16, v115
	v_and_b32_e32 v107, 0xffff0000, v115
	s_waitcnt lgkmcnt(0)
	v_pk_add_f32 v[108:109], v[108:109], v[110:111]
	ds_bpermute_b32 v111, v61, v109
	ds_bpermute_b32 v110, v61, v108
	s_waitcnt lgkmcnt(0)
	v_pk_add_f32 v[108:109], v[108:109], v[110:111]
	ds_bpermute_b32 v111, v75, v109
	ds_bpermute_b32 v110, v75, v108
	s_waitcnt lgkmcnt(0)
	v_pk_add_f32 v[108:109], v[108:109], v[110:111]
	ds_bpermute_b32 v111, v77, v109
	ds_bpermute_b32 v110, v77, v108
	s_waitcnt lgkmcnt(0)
	v_pk_add_f32 v[108:109], v[108:109], v[110:111]
	ds_bpermute_b32 v111, v94, v109
	ds_bpermute_b32 v110, v94, v108
	s_waitcnt lgkmcnt(0)
	v_pk_add_f32 v[108:109], v[108:109], v[110:111]
	ds_bpermute_b32 v111, v95, v109
	ds_bpermute_b32 v110, v95, v108
	s_waitcnt lgkmcnt(0)
	v_pk_add_f32 v[108:109], v[108:109], v[110:111]
	s_nop 0
	v_pk_fma_f32 v[108:109], v[108:109], s[8:9], v[60:61] op_sel_hi:[1,0,0]
	s_nop 0
	v_mul_f32_e32 v74, 0x4b800000, v109
	v_cmp_gt_f32_e64 s[0:1], s13, v109
	v_mul_f32_e32 v76, 0x4b800000, v108
	v_cmp_gt_f32_e32 vcc, s13, v108
	v_cndmask_b32_e64 v74, v109, v74, s[0:1]
	v_rsq_f32_e32 v74, v74
	v_cndmask_b32_e32 v76, v108, v76, vcc
	v_rsq_f32_e32 v108, v76
	v_mul_f32_e32 v76, 0x45800000, v74
	v_cndmask_b32_e64 v76, v74, v76, s[0:1]
	v_mul_f32_e32 v109, 0x45800000, v108
	v_cndmask_b32_e32 v74, v108, v109, vcc
	v_pk_mul_f32 v[108:109], v[76:77], v[124:125] op_sel_hi:[0,1]
	v_pk_mul_f32 v[110:111], v[76:77], v[126:127] op_sel_hi:[0,1]
	v_pk_mul_f32 v[112:113], v[76:77], v[128:129] op_sel_hi:[0,1]
	v_pk_mul_f32 v[114:115], v[76:77], v[130:131] op_sel_hi:[0,1]
	v_pk_mul_f32 v[124:125], v[74:75], v[206:207] op_sel_hi:[0,1]
	v_pk_mul_f32 v[126:127], v[74:75], v[208:209] op_sel_hi:[0,1]
	v_pk_mul_f32 v[128:129], v[74:75], v[210:211] op_sel_hi:[0,1]
	v_pk_mul_f32 v[130:131], v[74:75], v[212:213] op_sel_hi:[0,1]
	v_pk_mul_f32 v[108:109], v[6:7], v[108:109]
	v_pk_mul_f32 v[110:111], v[8:9], v[110:111]
	v_pk_mul_f32 v[112:113], v[2:3], v[112:113]
	v_pk_mul_f32 v[114:115], v[4:5], v[114:115]
	v_pk_mul_f32 v[124:125], v[6:7], v[124:125]
	v_pk_mul_f32 v[126:127], v[8:9], v[126:127]
	v_pk_mul_f32 v[128:129], v[2:3], v[128:129]
	v_pk_mul_f32 v[130:131], v[4:5], v[130:131]
	v_pk_fma_f32 v[2:3], v[120:121], v[108:109], v[194:195]
	v_pk_fma_f32 v[4:5], v[122:123], v[110:111], v[196:197]
	v_pk_fma_f32 v[6:7], v[116:117], v[112:113], v[198:199]
	v_pk_fma_f32 v[8:9], v[118:119], v[114:115], v[200:201]
	v_pk_fma_f32 v[100:101], v[120:121], v[124:125], v[100:101]
	v_pk_fma_f32 v[102:103], v[122:123], v[126:127], v[102:103]
	v_pk_fma_f32 v[104:105], v[116:117], v[128:129], v[104:105]
	v_pk_fma_f32 v[106:107], v[118:119], v[130:131], v[106:107]
	global_store_dwordx4 v[58:59], v[2:5], off nt
	global_store_dwordx4 v[58:59], v[6:9], off offset:16 nt
	global_store_dwordx4 v[62:63], v[100:103], off offset:-4096 nt
	global_store_dwordx4 v[64:65], v[104:107], off offset:16 nt
	global_load_dwordx4 v[2:5], v[50:51], off offset:2048
	s_nop 0
	global_load_dwordx4 v[6:9], v[50:51], off offset:2064
	global_load_dwordx4 v[100:103], v97, s[10:11]
	global_load_dwordx4 v[104:107], v97, s[10:11] offset:16
	v_pk_mul_f32 v[86:87], v[76:77], v[86:87] op_sel_hi:[0,1]
	v_pk_mul_f32 v[88:89], v[76:77], v[88:89] op_sel_hi:[0,1]
	v_lshlrev_b32_e32 v108, 16, v42
	v_and_b32_e32 v109, 0xffff0000, v42
	v_lshlrev_b32_e32 v42, 16, v43
	v_and_b32_e32 v43, 0xffff0000, v43
	v_pk_mul_f32 v[90:91], v[76:77], v[90:91] op_sel_hi:[0,1]
	v_pk_mul_f32 v[92:93], v[76:77], v[92:93] op_sel_hi:[0,1]
	v_pk_mul_f32 v[116:117], v[74:75], v[214:215] op_sel_hi:[0,1]
	v_pk_mul_f32 v[118:119], v[74:75], v[216:217] op_sel_hi:[0,1]
	v_pk_mul_f32 v[120:121], v[74:75], v[218:219] op_sel_hi:[0,1]
	v_pk_mul_f32 v[122:123], v[74:75], v[220:221] op_sel_hi:[0,1]
	v_lshlrev_b32_e32 v110, 16, v44
	v_and_b32_e32 v111, 0xffff0000, v44
	v_lshlrev_b32_e32 v44, 16, v45
	v_and_b32_e32 v45, 0xffff0000, v45
	v_lshlrev_b32_e32 v112, 16, v46
	v_and_b32_e32 v113, 0xffff0000, v46
	v_lshlrev_b32_e32 v46, 16, v47
	v_and_b32_e32 v47, 0xffff0000, v47
	v_lshlrev_b32_e32 v114, 16, v48
	v_and_b32_e32 v115, 0xffff0000, v48
	v_lshlrev_b32_e32 v48, 16, v49
	v_and_b32_e32 v49, 0xffff0000, v49
	v_pk_mul_f32 v[66:67], v[76:77], v[66:67] op_sel_hi:[0,1]
	v_pk_mul_f32 v[68:69], v[76:77], v[68:69] op_sel_hi:[0,1]
	v_pk_mul_f32 v[70:71], v[76:77], v[70:71] op_sel_hi:[0,1]
	v_pk_mul_f32 v[72:73], v[76:77], v[72:73] op_sel_hi:[0,1]
	v_pk_mul_f32 v[78:79], v[74:75], v[78:79] op_sel_hi:[0,1]
	v_pk_mul_f32 v[80:81], v[74:75], v[80:81] op_sel_hi:[0,1]
	v_pk_mul_f32 v[82:83], v[74:75], v[82:83] op_sel_hi:[0,1]
	v_pk_mul_f32 v[84:85], v[74:75], v[84:85] op_sel_hi:[0,1]
	v_pk_mul_f32 v[14:15], v[76:77], v[14:15] op_sel_hi:[0,1]
	v_pk_mul_f32 v[10:11], v[76:77], v[10:11] op_sel_hi:[0,1]
	v_pk_mul_f32 v[16:17], v[76:77], v[16:17] op_sel_hi:[0,1]
	v_pk_mul_f32 v[12:13], v[76:77], v[12:13] op_sel_hi:[0,1]
	v_pk_mul_f32 v[18:19], v[74:75], v[18:19] op_sel_hi:[0,1]
	v_pk_mul_f32 v[20:21], v[74:75], v[20:21] op_sel_hi:[0,1]
	v_pk_mul_f32 v[22:23], v[74:75], v[22:23] op_sel_hi:[0,1]
	v_pk_mul_f32 v[24:25], v[74:75], v[24:25] op_sel_hi:[0,1]
	s_waitcnt vmcnt(3)
	v_pk_mul_f32 v[86:87], v[2:3], v[86:87]
	v_pk_mul_f32 v[88:89], v[4:5], v[88:89]
	s_waitcnt vmcnt(2)
	v_pk_mul_f32 v[90:91], v[6:7], v[90:91]
	v_pk_mul_f32 v[92:93], v[8:9], v[92:93]
	v_pk_mul_f32 v[116:117], v[2:3], v[116:117]
	v_pk_mul_f32 v[118:119], v[4:5], v[118:119]
	v_pk_mul_f32 v[120:121], v[6:7], v[120:121]
	v_pk_mul_f32 v[122:123], v[8:9], v[122:123]
	s_waitcnt vmcnt(1)
	v_pk_fma_f32 v[2:3], v[100:101], v[86:87], v[108:109]
	v_pk_fma_f32 v[4:5], v[102:103], v[88:89], v[42:43]
	s_waitcnt vmcnt(0)
	v_pk_fma_f32 v[6:7], v[104:105], v[90:91], v[110:111]
	v_pk_fma_f32 v[8:9], v[106:107], v[92:93], v[44:45]
	v_pk_fma_f32 v[42:43], v[100:101], v[116:117], v[112:113]
	v_pk_fma_f32 v[44:45], v[102:103], v[118:119], v[46:47]
	v_pk_fma_f32 v[46:47], v[104:105], v[120:121], v[114:115]
	v_pk_fma_f32 v[48:49], v[106:107], v[122:123], v[48:49]
	global_store_dwordx4 v[58:59], v[2:5], off offset:2048 nt
	global_store_dwordx4 v[58:59], v[6:9], off offset:2064 nt
	global_store_dwordx4 v[64:65], v[42:45], off offset:2048 nt
	global_store_dwordx4 v[64:65], v[46:49], off offset:2064 nt
	s_mov_b64 s[16:17], exec
	v_readlane_b32 s18, v254, 2
	v_readlane_b32 s19, v254, 3
	s_nop 1
	s_mov_b64 exec, s[18:19]
	s_cbranch_execz .Lr4q_pre_skip
	buffer_inv sc1
	global_load_dword v238, v239, s[22:23] sc1
.Lr4q_pre_skip:
	s_mov_b64 exec, s[16:17]
	global_load_dwordx4 v[2:5], v[52:53], off
	s_nop 0
	global_load_dwordx4 v[6:9], v[52:53], off offset:16
	global_load_dwordx4 v[42:45], v98, s[10:11]
	global_load_dwordx4 v[46:49], v98, s[10:11] offset:16
	v_add_co_u32_e32 v64, vcc, s3, v58
	v_lshlrev_b32_e32 v86, 16, v34
	v_and_b32_e32 v87, 0xffff0000, v34
	v_lshlrev_b32_e32 v34, 16, v35
	v_and_b32_e32 v35, 0xffff0000, v35
	v_addc_co_u32_e32 v65, vcc, 0, v59, vcc
	v_lshlrev_b32_e32 v88, 16, v36
	v_and_b32_e32 v89, 0xffff0000, v36
	v_lshlrev_b32_e32 v36, 16, v37
	v_and_b32_e32 v37, 0xffff0000, v37
	v_lshlrev_b32_e32 v90, 16, v38
	v_and_b32_e32 v91, 0xffff0000, v38
	v_lshlrev_b32_e32 v38, 16, v39
	v_and_b32_e32 v39, 0xffff0000, v39
	v_lshlrev_b32_e32 v92, 16, v40
	v_and_b32_e32 v93, 0xffff0000, v40
	v_lshlrev_b32_e32 v40, 16, v41
	v_and_b32_e32 v41, 0xffff0000, v41
	v_lshl_add_u64 v[58:59], v[58:59], 0, s[6:7]
	s_waitcnt vmcnt(3)
	v_pk_mul_f32 v[66:67], v[2:3], v[66:67]
	v_pk_mul_f32 v[68:69], v[4:5], v[68:69]
	s_waitcnt vmcnt(2)
	v_pk_mul_f32 v[70:71], v[6:7], v[70:71]
	v_pk_mul_f32 v[72:73], v[8:9], v[72:73]
	v_pk_mul_f32 v[78:79], v[2:3], v[78:79]
	v_pk_mul_f32 v[80:81], v[4:5], v[80:81]
	v_pk_mul_f32 v[82:83], v[6:7], v[82:83]
	v_pk_mul_f32 v[84:85], v[8:9], v[84:85]
	s_waitcnt vmcnt(1)
	v_pk_fma_f32 v[2:3], v[42:43], v[66:67], v[86:87]
	v_pk_fma_f32 v[4:5], v[44:45], v[68:69], v[34:35]
	s_waitcnt vmcnt(0)
	v_pk_fma_f32 v[6:7], v[46:47], v[70:71], v[88:89]
	v_pk_fma_f32 v[8:9], v[48:49], v[72:73], v[36:37]
	v_pk_fma_f32 v[34:35], v[42:43], v[78:79], v[90:91]
	v_pk_fma_f32 v[36:37], v[44:45], v[80:81], v[38:39]
	v_pk_fma_f32 v[38:39], v[46:47], v[82:83], v[92:93]
	v_pk_fma_f32 v[40:41], v[48:49], v[84:85], v[40:41]
	global_store_dwordx4 v[64:65], v[2:5], off nt
	global_store_dwordx4 v[64:65], v[6:9], off offset:16 nt
	global_store_dwordx4 v[62:63], v[34:37], off nt
	global_store_dwordx4 v[62:63], v[38:41], off offset:16 nt
	global_load_dwordx4 v[2:5], v[54:55], off
	s_nop 0
	global_load_dwordx4 v[6:9], v[54:55], off offset:16
	global_load_dwordx4 v[34:37], v99, s[10:11]
	global_load_dwordx4 v[38:41], v99, s[10:11] offset:16
	v_lshlrev_b32_e32 v42, 16, v26
	v_and_b32_e32 v43, 0xffff0000, v26
	v_lshlrev_b32_e32 v26, 16, v27
	v_and_b32_e32 v27, 0xffff0000, v27
	v_lshlrev_b32_e32 v44, 16, v28
	v_and_b32_e32 v45, 0xffff0000, v28
	v_lshlrev_b32_e32 v28, 16, v29
	v_and_b32_e32 v29, 0xffff0000, v29
	v_lshlrev_b32_e32 v46, 16, v30
	v_and_b32_e32 v47, 0xffff0000, v30
	v_lshlrev_b32_e32 v30, 16, v31
	v_and_b32_e32 v31, 0xffff0000, v31
	v_lshlrev_b32_e32 v48, 16, v32
	v_and_b32_e32 v49, 0xffff0000, v32
	v_lshlrev_b32_e32 v32, 16, v33
	v_and_b32_e32 v33, 0xffff0000, v33
	s_waitcnt vmcnt(3)
	v_pk_mul_f32 v[14:15], v[14:15], v[2:3]
	v_pk_mul_f32 v[10:11], v[10:11], v[4:5]
	s_waitcnt vmcnt(2)
	v_pk_mul_f32 v[16:17], v[16:17], v[6:7]
	v_pk_mul_f32 v[12:13], v[12:13], v[8:9]
	v_pk_mul_f32 v[18:19], v[2:3], v[18:19]
	v_pk_mul_f32 v[20:21], v[4:5], v[20:21]
	v_pk_mul_f32 v[22:23], v[6:7], v[22:23]
	v_pk_mul_f32 v[24:25], v[8:9], v[24:25]
	s_waitcnt vmcnt(1)
	v_pk_fma_f32 v[2:3], v[14:15], v[34:35], v[42:43]
	v_pk_fma_f32 v[4:5], v[10:11], v[36:37], v[26:27]
	s_waitcnt vmcnt(0)
	v_pk_fma_f32 v[6:7], v[16:17], v[38:39], v[44:45]
	v_pk_fma_f32 v[8:9], v[12:13], v[40:41], v[28:29]
	v_pk_fma_f32 v[10:11], v[34:35], v[18:19], v[46:47]
	v_pk_fma_f32 v[12:13], v[36:37], v[20:21], v[30:31]
	v_pk_fma_f32 v[14:15], v[38:39], v[22:23], v[48:49]
	v_pk_fma_f32 v[16:17], v[40:41], v[24:25], v[32:33]
	global_store_dwordx4 v[64:65], v[2:5], off offset:2048 nt
	global_store_dwordx4 v[64:65], v[6:9], off offset:2064 nt
	global_store_dwordx4 v[62:63], v[10:13], off offset:2048 nt
	global_store_dwordx4 v[62:63], v[14:17], off offset:2064 nt
	v_mov_b32_e32 v1, v222
	v_mov_b32_e32 v138, v223
	v_mov_b32_e32 v139, v224
	v_mov_b32_e32 v140, v225
	v_mov_b32_e32 v141, v226
	v_mov_b32_e32 v142, v227
	v_mov_b32_e32 v143, v228
	v_mov_b32_e32 v144, v229
	v_mov_b32_e32 v145, v230
	v_mov_b32_e32 v154, v231
	v_mov_b32_e32 v155, v232
	v_mov_b32_e32 v156, v233
	v_mov_b32_e32 v157, v234
	v_mov_b32_e32 v158, v235
	v_mov_b32_e32 v159, v236
	v_mov_b32_e32 v160, v237
	v_readlane_b32 s0, v255, 40
	v_readlane_b32 s1, v255, 41
	v_readlane_b32 s2, v255, 42
	v_readlane_b32 s3, v255, 43
	v_readlane_b32 s6, v255, 44
	v_readlane_b32 s7, v255, 45
	v_readlane_b32 s25, v255, 46
	v_readlane_b32 s26, v255, 47
	v_readlane_b32 s27, v255, 48
	v_readlane_b32 s28, v255, 49
	v_readlane_b32 s49, v255, 50
	s_waitcnt vmcnt(0) lgkmcnt(0)
	s_mov_b64 s[8:9], exec
	v_readlane_b32 s10, v254, 2
	v_readlane_b32 s11, v254, 3
	s_nop 1
	s_and_b64 s[10:11], s[8:9], s[10:11]
	s_mov_b64 exec, s[10:11]
	s_cbranch_execz .Llb865_join
	v_mov_b32_e32 v4, 0x23fc4
	ds_read_b32 v3, v4
	s_waitcnt vmcnt(0) lgkmcnt(0)
	v_cmp_ge_u32_e32 vcc, v238, v3
	s_cbranch_vccnz .Llb865_join
	s_add_u32 s12, s62, 0x40d000
	s_addc_u32 s13, s63, 0
	v_mov_b32_e32 v4, 0x400
	s_mov_b32 s16, 0
	buffer_inv sc1

.LBB0_993:
	v_readlane_b32 s14, v254, 39
	s_cmp_lt_i32 s14, 13
	s_cselect_b64 s[2:3], -1, 0
	s_and_b64 s[0:1], s[2:3], s[0:1]
	s_cmpk_lt_i32 s44, 0x2000
	s_cselect_b64 s[2:3], -1, 0
	s_and_b64 s[0:1], s[0:1], s[2:3]
	v_readlane_b32 s15, v254, 40
	s_movk_i32 s9, 0x2000
	s_and_b64 vcc, exec, s[0:1]
	s_cbranch_vccz .LBB0_996
	v_mbcnt_lo_u32_b32 v1, -1, 0
	v_mbcnt_hi_u32_b32 v3, -1, v1
	v_and_b32_e32 v1, 64, v3
	v_add_u32_e32 v4, 64, v1
	v_xor_b32_e32 v1, 1, v3
	v_cmp_lt_i32_e32 vcc, v1, v4
	v_xor_b32_e32 v6, 2, v3
	s_lshl_b32 s2, s44, 1
	v_cndmask_b32_e32 v1, v3, v1, vcc
	v_cmp_lt_i32_e32 vcc, v6, v4
	v_lshlrev_b32_e32 v2, 3, v191
	v_mov_b32_e32 v5, 0
	v_cndmask_b32_e32 v6, v3, v6, vcc
	v_lshlrev_b32_e32 v61, 2, v6
	v_xor_b32_e32 v6, 4, v3
	v_cmp_lt_i32_e32 vcc, v6, v4
	v_or_b32_e32 v8, 0x400, v2
	s_ashr_i32 s3, s2, 31
	v_cndmask_b32_e32 v6, v3, v6, vcc
	v_lshlrev_b32_e32 v75, 2, v6
	v_xor_b32_e32 v6, 8, v3
	v_cmp_lt_i32_e32 vcc, v6, v4
	v_or_b32_e32 v10, 0x600, v2
	v_lshlrev_b32_e32 v12, 2, v8
	v_cndmask_b32_e32 v6, v3, v6, vcc
	v_mov_b32_e32 v13, v5
	s_lshl_b64 s[0:1], s[2:3], 12
	v_lshlrev_b32_e32 v77, 2, v6
	v_xor_b32_e32 v6, 16, v3
	v_lshl_add_u64 v[52:53], s[58:59], 0, v[12:13]
	v_lshlrev_b32_e32 v12, 2, v10
	s_add_u32 s0, s62, s0
	v_cmp_lt_i32_e32 vcc, v6, v4
	v_lshl_add_u64 v[54:55], s[58:59], 0, v[12:13]
	v_lshlrev_b32_e32 v12, 4, v191
	s_addc_u32 s1, s63, s1
	v_cndmask_b32_e32 v6, v3, v6, vcc
	v_lshl_add_u64 v[12:13], s[0:1], 0, v[12:13]
	s_mov_b64 s[0:1], 0x10800000
	s_ashr_i32 s49, s48, 31
	v_lshlrev_b32_e32 v94, 2, v6
	v_xor_b32_e32 v6, 32, v3
	v_lshl_add_u64 v[56:57], v[12:13], 0, s[0:1]
	s_lshl_b64 s[4:5], s[48:49], 12
	s_lshl_b64 s[0:1], s[2:3], 13
	v_cmp_lt_i32_e32 vcc, v6, v4
	s_add_u32 s0, s60, s0
	v_lshlrev_b32_e32 v4, 5, v191
	v_cndmask_b32_e32 v3, v3, v6, vcc
	v_or_b32_e32 v6, 0x200, v2
	s_addc_u32 s1, s61, s1
	v_lshlrev_b32_e32 v1, 2, v1
	v_lshlrev_b32_e32 v95, 2, v3
	v_lshl_add_u64 v[50:51], s[58:59], 0, v[4:5]
	v_lshl_add_u64 v[58:59], s[0:1], 0, v[4:5]
	s_lshl_b64 s[6:7], s[48:49], 13
	s_movk_i32 s3, 0x1000
	s_mov_b32 s12, 0x4001000
	v_lshlrev_b32_e32 v96, 2, v2
	v_lshlrev_b32_e32 v97, 2, v6
	v_lshlrev_b32_e32 v98, 2, v8
	v_lshlrev_b32_e32 v99, 2, v10
	s_mov_b32 s8, 0x3a000000
	s_mov_b32 s13, 0x800000
	s_movk_i32 s14, 0x3000
	v_mov_b32_e32 v60, 0x358637bd
	s_add_i32 s2, s2, s48
	v_lshl_add_u64 v[56:57], v[56:57], 0, s[4:5]
	v_lshl_add_u64 v[58:59], v[58:59], 0, s[6:7]
	s_add_u32 s26, s62, 0x408000
	s_addc_u32 s27, s63, 0
	v_mov_b32_e32 v239, 0x400
	v_mov_b32_e32 v238, 0
	s_mov_b32 s20, 0
.LBB0_995:
	s_cmp_lg_u32 s20, 1
	s_cbranch_scc1 .Lr4_nowait
	s_cmp_eq_u32 s21, 0
	s_cbranch_scc1 .Lr4_nowait
	s_mov_b64 s[22:23], exec
	v_readlane_b32 s24, v254, 2
	v_readlane_b32 s25, v254, 3
	s_nop 1
	s_and_b64 s[24:25], s[22:23], s[24:25]
	s_mov_b64 exec, s[24:25]
	s_cbranch_execz .Lr4_wait_join
	v_mov_b32_e32 v2, 0x23fc4
	ds_read_b32 v3, v2
	s_waitcnt vmcnt(0) lgkmcnt(0)
	v_cmp_ge_u32_e32 vcc, v238, v3
	s_cbranch_vccnz .Lr4_wait_join
	s_add_u32 s26, s62, 0x408000
	s_addc_u32 s27, s63, 0
	v_mov_b32_e32 v2, 0x400
	s_mov_b32 s28, 0
	buffer_inv sc1

.Lr4_nowait:
	s_add_u32 s20, s20, 1
	v_add_co_u32_e32 v30, vcc, 0x4000000, v56
	global_load_dwordx4 v[22:25], v[56:57], off
	global_load_dwordx4 v[18:21], v[56:57], off offset:1024
	global_load_dwordx4 v[14:17], v[56:57], off offset:2048
	global_load_dwordx4 v[10:13], v[56:57], off offset:3072
	v_addc_co_u32_e32 v31, vcc, 0, v57, vcc
	v_add_co_u32_e32 v32, vcc, s3, v56
	global_load_dwordx4 v[2:5], v[50:51], off offset:16
	global_load_dwordx4 v[6:9], v[50:51], off
	v_addc_co_u32_e32 v33, vcc, 0, v57, vcc
	global_load_dwordx4 v[78:81], v[30:31], off
	global_load_dwordx4 v[42:45], v[30:31], off offset:1024
	global_load_dwordx4 v[34:37], v[30:31], off offset:2048
	global_load_dwordx4 v[26:29], v[30:31], off offset:3072
	global_load_dwordx4 v[82:85], v[32:33], off
	global_load_dwordx4 v[100:103], v[32:33], off offset:1024
	global_load_dwordx4 v[104:107], v[32:33], off offset:2048
	global_load_dwordx4 v[108:111], v[32:33], off offset:3072
	v_add_co_u32_e32 v66, vcc, s12, v56
	v_add_co_u32_e64 v64, s[0:1], s9, v58
	s_nop 0
	v_addc_co_u32_e32 v67, vcc, 0, v57, vcc
	global_load_dwordx4 v[112:115], v[66:67], off
	global_load_dwordx4 v[46:49], v[66:67], off offset:1024
	global_load_dwordx4 v[38:41], v[66:67], off offset:2048
	global_load_dwordx4 v[30:33], v[66:67], off offset:3072
	v_addc_co_u32_e64 v65, s[0:1], 0, v59, s[0:1]
	v_add_co_u32_e64 v62, s[0:1], s14, v58
	s_add_i32 s10, s2, 0xffffe000
	s_nop 0
	v_addc_co_u32_e64 v63, s[0:1], 0, v59, s[0:1]
	s_lshr_b32 s0, s10, 10
	s_add_i32 s0, s0, 1
	s_cmpk_gt_i32 s2, 0x1fff
	s_cselect_b32 s0, s0, 0
	s_mul_hi_u32 s1, s0, 0xc000
	s_mul_i32 s0, s0, 0xc000
	s_add_u32 s0, s62, s0
	s_addc_u32 s1, s63, s1
	s_add_u32 s10, s0, 0xa000
	s_addc_u32 s11, s1, 0
	global_load_dwordx4 v[116:119], v96, s[10:11] offset:16
	global_load_dwordx4 v[120:123], v96, s[10:11]
	s_add_i32 s2, s2, s48
	v_lshl_add_u64 v[56:57], v[56:57], 0, s[4:5]
	s_cmpk_lt_i32 s2, 0x4000
	s_waitcnt vmcnt(0)
	v_and_b32_e32 v125, 0xffff0000, v22
	v_lshlrev_b32_e32 v124, 16, v22
	v_lshlrev_b32_e32 v126, 16, v23
	v_and_b32_e32 v127, 0xffff0000, v23
	v_lshlrev_b32_e32 v70, 16, v16
	v_and_b32_e32 v71, 0xffff0000, v16
	v_lshlrev_b32_e32 v72, 16, v17
	v_and_b32_e32 v73, 0xffff0000, v17
	v_lshlrev_b32_e32 v16, 16, v12
	v_and_b32_e32 v207, 0xffff0000, v82
	v_and_b32_e32 v17, 0xffff0000, v12
	v_mov_b32_e32 v137, v125
	v_lshlrev_b32_e32 v206, 16, v82
	v_lshlrev_b32_e32 v22, 16, v110
	v_and_b32_e32 v23, 0xffff0000, v110
	v_mov_b32_e32 v136, v207
	v_lshlrev_b32_e32 v86, 16, v18
	v_and_b32_e32 v87, 0xffff0000, v18
	v_lshlrev_b32_e32 v88, 16, v19
	v_and_b32_e32 v89, 0xffff0000, v19
	v_lshlrev_b32_e32 v90, 16, v20
	v_and_b32_e32 v91, 0xffff0000, v20
	v_lshlrev_b32_e32 v92, 16, v21
	v_and_b32_e32 v93, 0xffff0000, v21
	v_mov_b32_e32 v135, v124
	v_pk_mul_f32 v[170:171], v[16:17], v[16:17]
	v_lshlrev_b32_e32 v208, 16, v83
	v_lshlrev_b32_e32 v214, 16, v100
	v_and_b32_e32 v215, 0xffff0000, v100
	v_lshlrev_b32_e32 v216, 16, v101
	v_and_b32_e32 v217, 0xffff0000, v101
	v_lshlrev_b32_e32 v218, 16, v102
	v_and_b32_e32 v219, 0xffff0000, v102
	v_lshlrev_b32_e32 v220, 16, v103
	v_and_b32_e32 v221, 0xffff0000, v103
	v_lshlrev_b32_e32 v18, 16, v108
	v_and_b32_e32 v19, 0xffff0000, v108
	v_lshlrev_b32_e32 v20, 16, v109
	v_and_b32_e32 v21, 0xffff0000, v109
	v_lshlrev_b32_e32 v100, 16, v112
	v_and_b32_e32 v101, 0xffff0000, v112
	v_lshlrev_b32_e32 v102, 16, v113
	v_and_b32_e32 v103, 0xffff0000, v113
	v_mov_b32_e32 v134, v206
	v_pk_mul_f32 v[108:109], v[22:23], v[22:23]
	v_pk_mul_f32 v[112:113], v[136:137], v[136:137]
	v_mov_b32_e32 v139, v126
	v_mov_b32_e32 v203, v170
	v_and_b32_e32 v209, 0xffff0000, v83
	v_mov_b32_e32 v138, v208
	v_mov_b32_e32 v202, v108
	v_mov_b32_e32 v170, v109
	v_pk_fma_f32 v[108:109], v[134:135], v[134:135], v[112:113]
	v_lshlrev_b32_e32 v128, 16, v24
	v_mov_b32_e32 v141, v127
	v_lshlrev_b32_e32 v210, 16, v84
	v_mov_b32_e32 v140, v209
	v_pk_fma_f32 v[108:109], v[138:139], v[138:139], v[108:109]
	v_and_b32_e32 v129, 0xffff0000, v24
	v_mov_b32_e32 v143, v128
	v_and_b32_e32 v211, 0xffff0000, v84
	v_mov_b32_e32 v142, v210
	v_pk_fma_f32 v[108:109], v[140:141], v[140:141], v[108:109]
	v_lshlrev_b32_e32 v130, 16, v25
	v_mov_b32_e32 v145, v129
	v_lshlrev_b32_e32 v212, 16, v85
	v_mov_b32_e32 v144, v211
	v_pk_fma_f32 v[108:109], v[142:143], v[142:143], v[108:109]
	v_and_b32_e32 v131, 0xffff0000, v25
	v_mov_b32_e32 v147, v130
	v_and_b32_e32 v213, 0xffff0000, v85
	v_mov_b32_e32 v146, v212
	v_pk_fma_f32 v[108:109], v[144:145], v[144:145], v[108:109]
	v_mov_b32_e32 v133, v131
	v_mov_b32_e32 v132, v213
	v_pk_fma_f32 v[108:109], v[146:147], v[146:147], v[108:109]
	v_mov_b32_e32 v149, v86
	v_mov_b32_e32 v148, v214
	v_pk_fma_f32 v[108:109], v[132:133], v[132:133], v[108:109]
	v_mov_b32_e32 v151, v87
	v_mov_b32_e32 v150, v215
	v_pk_fma_f32 v[108:109], v[148:149], v[148:149], v[108:109]
	v_mov_b32_e32 v153, v88
	v_mov_b32_e32 v152, v216
	v_pk_fma_f32 v[108:109], v[150:151], v[150:151], v[108:109]
	v_mov_b32_e32 v155, v89
	v_mov_b32_e32 v154, v217
	v_pk_fma_f32 v[108:109], v[152:153], v[152:153], v[108:109]
	v_mov_b32_e32 v157, v90
	v_mov_b32_e32 v156, v218
	v_pk_fma_f32 v[108:109], v[154:155], v[154:155], v[108:109]
	v_mov_b32_e32 v159, v91
	v_mov_b32_e32 v158, v219
	v_pk_fma_f32 v[108:109], v[156:157], v[156:157], v[108:109]
	v_mov_b32_e32 v161, v92
	v_mov_b32_e32 v160, v220
	v_pk_fma_f32 v[108:109], v[158:159], v[158:159], v[108:109]
	v_lshlrev_b32_e32 v66, 16, v14
	v_mov_b32_e32 v163, v93
	v_lshlrev_b32_e32 v194, 16, v78
	v_and_b32_e32 v195, 0xffff0000, v78
	v_lshlrev_b32_e32 v78, 16, v104
	v_mov_b32_e32 v162, v221
	v_pk_fma_f32 v[108:109], v[160:161], v[160:161], v[108:109]
	v_and_b32_e32 v67, 0xffff0000, v14
	v_mov_b32_e32 v165, v66
	v_lshlrev_b32_e32 v196, 16, v79
	v_and_b32_e32 v197, 0xffff0000, v79
	v_and_b32_e32 v79, 0xffff0000, v104
	v_mov_b32_e32 v164, v78
	v_pk_fma_f32 v[108:109], v[162:163], v[162:163], v[108:109]
	v_lshlrev_b32_e32 v68, 16, v15
	v_mov_b32_e32 v167, v67
	v_lshlrev_b32_e32 v198, 16, v80
	v_and_b32_e32 v199, 0xffff0000, v80
	v_lshlrev_b32_e32 v80, 16, v105
	v_mov_b32_e32 v166, v79
	v_pk_fma_f32 v[108:109], v[164:165], v[164:165], v[108:109]
	v_and_b32_e32 v69, 0xffff0000, v15
	v_mov_b32_e32 v169, v68
	v_lshlrev_b32_e32 v200, 16, v81
	v_and_b32_e32 v201, 0xffff0000, v81
	v_and_b32_e32 v81, 0xffff0000, v105
	v_mov_b32_e32 v168, v80
	v_pk_fma_f32 v[108:109], v[166:167], v[166:167], v[108:109]
	v_mov_b32_e32 v175, v69
	v_lshlrev_b32_e32 v82, 16, v106
	v_mov_b32_e32 v174, v81
	v_pk_fma_f32 v[108:109], v[168:169], v[168:169], v[108:109]
	v_mov_b32_e32 v177, v70
	v_and_b32_e32 v83, 0xffff0000, v106
	v_mov_b32_e32 v176, v82
	v_pk_fma_f32 v[108:109], v[174:175], v[174:175], v[108:109]
	v_mov_b32_e32 v179, v71
	v_lshlrev_b32_e32 v84, 16, v107
	v_mov_b32_e32 v178, v83
	v_pk_fma_f32 v[108:109], v[176:177], v[176:177], v[108:109]
	v_mov_b32_e32 v181, v72
	v_and_b32_e32 v85, 0xffff0000, v107
	v_mov_b32_e32 v180, v84
	v_pk_fma_f32 v[108:109], v[178:179], v[178:179], v[108:109]
	v_lshlrev_b32_e32 v14, 16, v10
	v_mov_b32_e32 v183, v73
	v_mov_b32_e32 v182, v85
	v_pk_fma_f32 v[108:109], v[180:181], v[180:181], v[108:109]
	v_and_b32_e32 v15, 0xffff0000, v10
	v_mov_b32_e32 v185, v14
	v_mov_b32_e32 v184, v18
	v_pk_fma_f32 v[108:109], v[182:183], v[182:183], v[108:109]
	v_lshlrev_b32_e32 v10, 16, v11
	v_mov_b32_e32 v187, v15
	v_mov_b32_e32 v186, v19
	v_pk_fma_f32 v[108:109], v[184:185], v[184:185], v[108:109]
	v_and_b32_e32 v11, 0xffff0000, v11
	v_mov_b32_e32 v189, v10
	v_mov_b32_e32 v188, v20
	v_pk_fma_f32 v[108:109], v[186:187], v[186:187], v[108:109]
	v_mov_b32_e32 v193, v11
	v_mov_b32_e32 v192, v21
	v_pk_fma_f32 v[108:109], v[188:189], v[188:189], v[108:109]
	v_lshlrev_b32_e32 v12, 16, v13
	v_and_b32_e32 v13, 0xffff0000, v13
	v_lshlrev_b32_e32 v24, 16, v111
	v_and_b32_e32 v25, 0xffff0000, v111
	v_pk_fma_f32 v[108:109], v[192:193], v[192:193], v[108:109]
	v_pk_mul_f32 v[172:173], v[12:13], v[12:13]
	v_pk_mul_f32 v[110:111], v[24:25], v[24:25]
	v_pk_add_f32 v[108:109], v[202:203], v[108:109]
	v_mov_b32_e32 v205, v172
	v_mov_b32_e32 v204, v110
	v_pk_add_f32 v[108:109], v[170:171], v[108:109]
	v_mov_b32_e32 v172, v111
	v_pk_add_f32 v[108:109], v[204:205], v[108:109]
	v_lshlrev_b32_e32 v104, 16, v114
	v_pk_add_f32 v[108:109], v[172:173], v[108:109]
	ds_bpermute_b32 v111, v1, v109
	ds_bpermute_b32 v110, v1, v108
	v_and_b32_e32 v105, 0xffff0000, v114
	v_lshlrev_b32_e32 v106, 16, v115
	v_and_b32_e32 v107, 0xffff0000, v115
	s_waitcnt lgkmcnt(0)
	v_pk_add_f32 v[108:109], v[108:109], v[110:111]
	ds_bpermute_b32 v111, v61, v109
	ds_bpermute_b32 v110, v61, v108
	s_waitcnt lgkmcnt(0)
	v_pk_add_f32 v[108:109], v[108:109], v[110:111]
	ds_bpermute_b32 v111, v75, v109
	ds_bpermute_b32 v110, v75, v108
	s_waitcnt lgkmcnt(0)
	v_pk_add_f32 v[108:109], v[108:109], v[110:111]
	ds_bpermute_b32 v111, v77, v109
	ds_bpermute_b32 v110, v77, v108
	s_waitcnt lgkmcnt(0)
	v_pk_add_f32 v[108:109], v[108:109], v[110:111]
	ds_bpermute_b32 v111, v94, v109
	ds_bpermute_b32 v110, v94, v108
	s_waitcnt lgkmcnt(0)
	v_pk_add_f32 v[108:109], v[108:109], v[110:111]
	ds_bpermute_b32 v111, v95, v109
	ds_bpermute_b32 v110, v95, v108
	s_waitcnt lgkmcnt(0)
	v_pk_add_f32 v[108:109], v[108:109], v[110:111]
	s_nop 0
	v_pk_fma_f32 v[108:109], v[108:109], s[8:9], v[60:61] op_sel_hi:[1,0,0]
	s_nop 0
	v_mul_f32_e32 v74, 0x4b800000, v109
	v_cmp_gt_f32_e64 s[0:1], s13, v109
	v_mul_f32_e32 v76, 0x4b800000, v108
	v_cmp_gt_f32_e32 vcc, s13, v108
	v_cndmask_b32_e64 v74, v109, v74, s[0:1]
	v_rsq_f32_e32 v74, v74
	v_cndmask_b32_e32 v76, v108, v76, vcc
	v_rsq_f32_e32 v108, v76
	v_mul_f32_e32 v76, 0x45800000, v74
	v_cndmask_b32_e64 v76, v74, v76, s[0:1]
	v_mul_f32_e32 v109, 0x45800000, v108
	v_cndmask_b32_e32 v74, v108, v109, vcc
	v_pk_mul_f32 v[108:109], v[76:77], v[124:125] op_sel_hi:[0,1]
	v_pk_mul_f32 v[110:111], v[76:77], v[126:127] op_sel_hi:[0,1]
	v_pk_mul_f32 v[112:113], v[76:77], v[128:129] op_sel_hi:[0,1]
	v_pk_mul_f32 v[114:115], v[76:77], v[130:131] op_sel_hi:[0,1]
	v_pk_mul_f32 v[124:125], v[74:75], v[206:207] op_sel_hi:[0,1]
	v_pk_mul_f32 v[126:127], v[74:75], v[208:209] op_sel_hi:[0,1]
	v_pk_mul_f32 v[128:129], v[74:75], v[210:211] op_sel_hi:[0,1]
	v_pk_mul_f32 v[130:131], v[74:75], v[212:213] op_sel_hi:[0,1]
	v_pk_mul_f32 v[108:109], v[6:7], v[108:109]
	v_pk_mul_f32 v[110:111], v[8:9], v[110:111]
	v_pk_mul_f32 v[112:113], v[2:3], v[112:113]
	v_pk_mul_f32 v[114:115], v[4:5], v[114:115]
	v_pk_mul_f32 v[124:125], v[6:7], v[124:125]
	v_pk_mul_f32 v[126:127], v[8:9], v[126:127]
	v_pk_mul_f32 v[128:129], v[2:3], v[128:129]
	v_pk_mul_f32 v[130:131], v[4:5], v[130:131]
	v_pk_fma_f32 v[2:3], v[120:121], v[108:109], v[194:195]
	v_pk_fma_f32 v[4:5], v[122:123], v[110:111], v[196:197]
	v_pk_fma_f32 v[6:7], v[116:117], v[112:113], v[198:199]
	v_pk_fma_f32 v[8:9], v[118:119], v[114:115], v[200:201]
	v_pk_fma_f32 v[100:101], v[120:121], v[124:125], v[100:101]
	v_pk_fma_f32 v[102:103], v[122:123], v[126:127], v[102:103]
	v_pk_fma_f32 v[104:105], v[116:117], v[128:129], v[104:105]
	v_pk_fma_f32 v[106:107], v[118:119], v[130:131], v[106:107]
	global_store_dwordx4 v[58:59], v[2:5], off nt
	global_store_dwordx4 v[58:59], v[6:9], off offset:16 nt
	global_store_dwordx4 v[62:63], v[100:103], off offset:-4096 nt
	global_store_dwordx4 v[64:65], v[104:107], off offset:16 nt
	global_load_dwordx4 v[2:5], v[50:51], off offset:2048
	s_nop 0
	global_load_dwordx4 v[6:9], v[50:51], off offset:2064
	global_load_dwordx4 v[100:103], v97, s[10:11]
	global_load_dwordx4 v[104:107], v97, s[10:11] offset:16
	v_pk_mul_f32 v[86:87], v[76:77], v[86:87] op_sel_hi:[0,1]
	v_pk_mul_f32 v[88:89], v[76:77], v[88:89] op_sel_hi:[0,1]
	v_lshlrev_b32_e32 v108, 16, v42
	v_and_b32_e32 v109, 0xffff0000, v42
	v_lshlrev_b32_e32 v42, 16, v43
	v_and_b32_e32 v43, 0xffff0000, v43
	v_pk_mul_f32 v[90:91], v[76:77], v[90:91] op_sel_hi:[0,1]
	v_pk_mul_f32 v[92:93], v[76:77], v[92:93] op_sel_hi:[0,1]
	v_pk_mul_f32 v[116:117], v[74:75], v[214:215] op_sel_hi:[0,1]
	v_pk_mul_f32 v[118:119], v[74:75], v[216:217] op_sel_hi:[0,1]
	v_pk_mul_f32 v[120:121], v[74:75], v[218:219] op_sel_hi:[0,1]
	v_pk_mul_f32 v[122:123], v[74:75], v[220:221] op_sel_hi:[0,1]
	v_lshlrev_b32_e32 v110, 16, v44
	v_and_b32_e32 v111, 0xffff0000, v44
	v_lshlrev_b32_e32 v44, 16, v45
	v_and_b32_e32 v45, 0xffff0000, v45
	v_lshlrev_b32_e32 v112, 16, v46
	v_and_b32_e32 v113, 0xffff0000, v46
	v_lshlrev_b32_e32 v46, 16, v47
	v_and_b32_e32 v47, 0xffff0000, v47
	v_lshlrev_b32_e32 v114, 16, v48
	v_and_b32_e32 v115, 0xffff0000, v48
	v_lshlrev_b32_e32 v48, 16, v49
	v_and_b32_e32 v49, 0xffff0000, v49
	v_pk_mul_f32 v[66:67], v[76:77], v[66:67] op_sel_hi:[0,1]
	v_pk_mul_f32 v[68:69], v[76:77], v[68:69] op_sel_hi:[0,1]
	v_pk_mul_f32 v[70:71], v[76:77], v[70:71] op_sel_hi:[0,1]
	v_pk_mul_f32 v[72:73], v[76:77], v[72:73] op_sel_hi:[0,1]
	v_pk_mul_f32 v[78:79], v[74:75], v[78:79] op_sel_hi:[0,1]
	v_pk_mul_f32 v[80:81], v[74:75], v[80:81] op_sel_hi:[0,1]
	v_pk_mul_f32 v[82:83], v[74:75], v[82:83] op_sel_hi:[0,1]
	v_pk_mul_f32 v[84:85], v[74:75], v[84:85] op_sel_hi:[0,1]
	v_pk_mul_f32 v[14:15], v[76:77], v[14:15] op_sel_hi:[0,1]
	v_pk_mul_f32 v[10:11], v[76:77], v[10:11] op_sel_hi:[0,1]
	v_pk_mul_f32 v[16:17], v[76:77], v[16:17] op_sel_hi:[0,1]
	v_pk_mul_f32 v[12:13], v[76:77], v[12:13] op_sel_hi:[0,1]
	v_pk_mul_f32 v[18:19], v[74:75], v[18:19] op_sel_hi:[0,1]
	v_pk_mul_f32 v[20:21], v[74:75], v[20:21] op_sel_hi:[0,1]
	v_pk_mul_f32 v[22:23], v[74:75], v[22:23] op_sel_hi:[0,1]
	v_pk_mul_f32 v[24:25], v[74:75], v[24:25] op_sel_hi:[0,1]
	s_waitcnt vmcnt(3)
	v_pk_mul_f32 v[86:87], v[2:3], v[86:87]
	v_pk_mul_f32 v[88:89], v[4:5], v[88:89]
	s_waitcnt vmcnt(2)
	v_pk_mul_f32 v[90:91], v[6:7], v[90:91]
	v_pk_mul_f32 v[92:93], v[8:9], v[92:93]
	v_pk_mul_f32 v[116:117], v[2:3], v[116:117]
	v_pk_mul_f32 v[118:119], v[4:5], v[118:119]
	v_pk_mul_f32 v[120:121], v[6:7], v[120:121]
	v_pk_mul_f32 v[122:123], v[8:9], v[122:123]
	s_waitcnt vmcnt(1)
	v_pk_fma_f32 v[2:3], v[100:101], v[86:87], v[108:109]
	v_pk_fma_f32 v[4:5], v[102:103], v[88:89], v[42:43]
	s_waitcnt vmcnt(0)
	v_pk_fma_f32 v[6:7], v[104:105], v[90:91], v[110:111]
	v_pk_fma_f32 v[8:9], v[106:107], v[92:93], v[44:45]
	v_pk_fma_f32 v[42:43], v[100:101], v[116:117], v[112:113]
	v_pk_fma_f32 v[44:45], v[102:103], v[118:119], v[46:47]
	v_pk_fma_f32 v[46:47], v[104:105], v[120:121], v[114:115]
	v_pk_fma_f32 v[48:49], v[106:107], v[122:123], v[48:49]
	global_store_dwordx4 v[58:59], v[2:5], off offset:2048 nt
	global_store_dwordx4 v[58:59], v[6:9], off offset:2064 nt
	global_store_dwordx4 v[64:65], v[42:45], off offset:2048 nt
	global_store_dwordx4 v[64:65], v[46:49], off offset:2064 nt
	s_mov_b64 s[22:23], exec
	v_readlane_b32 s24, v254, 2
	v_readlane_b32 s25, v254, 3
	s_nop 1
	s_mov_b64 exec, s[24:25]
	s_cbranch_execz .Lr4pre_skip
	v_cmp_eq_u32_e64 s[24:25], s20, 1
	s_nop 1
	s_mov_b64 exec, s[24:25]
	s_cbranch_execz .Lr4pre_skip
	buffer_inv sc1
	global_load_dword v238, v239, s[26:27] sc1
.Lr4pre_skip:
	s_mov_b64 exec, s[22:23]
	global_load_dwordx4 v[2:5], v[52:53], off
	s_nop 0
	global_load_dwordx4 v[6:9], v[52:53], off offset:16
	global_load_dwordx4 v[42:45], v98, s[10:11]
	global_load_dwordx4 v[46:49], v98, s[10:11] offset:16
	v_add_co_u32_e32 v64, vcc, s3, v58
	v_lshlrev_b32_e32 v86, 16, v34
	v_and_b32_e32 v87, 0xffff0000, v34
	v_lshlrev_b32_e32 v34, 16, v35
	v_and_b32_e32 v35, 0xffff0000, v35
	v_addc_co_u32_e32 v65, vcc, 0, v59, vcc
	v_lshlrev_b32_e32 v88, 16, v36
	v_and_b32_e32 v89, 0xffff0000, v36
	v_lshlrev_b32_e32 v36, 16, v37
	v_and_b32_e32 v37, 0xffff0000, v37
	v_lshlrev_b32_e32 v90, 16, v38
	v_and_b32_e32 v91, 0xffff0000, v38
	v_lshlrev_b32_e32 v38, 16, v39
	v_and_b32_e32 v39, 0xffff0000, v39
	v_lshlrev_b32_e32 v92, 16, v40
	v_and_b32_e32 v93, 0xffff0000, v40
	v_lshlrev_b32_e32 v40, 16, v41
	v_and_b32_e32 v41, 0xffff0000, v41
	v_lshl_add_u64 v[58:59], v[58:59], 0, s[6:7]
	s_waitcnt vmcnt(3)
	v_pk_mul_f32 v[66:67], v[2:3], v[66:67]
	v_pk_mul_f32 v[68:69], v[4:5], v[68:69]
	s_waitcnt vmcnt(2)
	v_pk_mul_f32 v[70:71], v[6:7], v[70:71]
	v_pk_mul_f32 v[72:73], v[8:9], v[72:73]
	v_pk_mul_f32 v[78:79], v[2:3], v[78:79]
	v_pk_mul_f32 v[80:81], v[4:5], v[80:81]
	v_pk_mul_f32 v[82:83], v[6:7], v[82:83]
	v_pk_mul_f32 v[84:85], v[8:9], v[84:85]
	s_waitcnt vmcnt(1)
	v_pk_fma_f32 v[2:3], v[42:43], v[66:67], v[86:87]
	v_pk_fma_f32 v[4:5], v[44:45], v[68:69], v[34:35]
	s_waitcnt vmcnt(0)
	v_pk_fma_f32 v[6:7], v[46:47], v[70:71], v[88:89]
	v_pk_fma_f32 v[8:9], v[48:49], v[72:73], v[36:37]
	v_pk_fma_f32 v[34:35], v[42:43], v[78:79], v[90:91]
	v_pk_fma_f32 v[36:37], v[44:45], v[80:81], v[38:39]
	v_pk_fma_f32 v[38:39], v[46:47], v[82:83], v[92:93]
	v_pk_fma_f32 v[40:41], v[48:49], v[84:85], v[40:41]
	global_store_dwordx4 v[64:65], v[2:5], off nt
	global_store_dwordx4 v[64:65], v[6:9], off offset:16 nt
	global_store_dwordx4 v[62:63], v[34:37], off nt
	global_store_dwordx4 v[62:63], v[38:41], off offset:16 nt
	global_load_dwordx4 v[2:5], v[54:55], off
	s_nop 0
	global_load_dwordx4 v[6:9], v[54:55], off offset:16
	global_load_dwordx4 v[34:37], v99, s[10:11]
	global_load_dwordx4 v[38:41], v99, s[10:11] offset:16
	v_lshlrev_b32_e32 v42, 16, v26
	v_and_b32_e32 v43, 0xffff0000, v26
	v_lshlrev_b32_e32 v26, 16, v27
	v_and_b32_e32 v27, 0xffff0000, v27
	v_lshlrev_b32_e32 v44, 16, v28
	v_and_b32_e32 v45, 0xffff0000, v28
	v_lshlrev_b32_e32 v28, 16, v29
	v_and_b32_e32 v29, 0xffff0000, v29
	v_lshlrev_b32_e32 v46, 16, v30
	v_and_b32_e32 v47, 0xffff0000, v30
	v_lshlrev_b32_e32 v30, 16, v31
	v_and_b32_e32 v31, 0xffff0000, v31
	v_lshlrev_b32_e32 v48, 16, v32
	v_and_b32_e32 v49, 0xffff0000, v32
	v_lshlrev_b32_e32 v32, 16, v33
	v_and_b32_e32 v33, 0xffff0000, v33
	s_waitcnt vmcnt(3)
	v_pk_mul_f32 v[14:15], v[14:15], v[2:3]
	v_pk_mul_f32 v[10:11], v[10:11], v[4:5]
	s_waitcnt vmcnt(2)
	v_pk_mul_f32 v[16:17], v[16:17], v[6:7]
	v_pk_mul_f32 v[12:13], v[12:13], v[8:9]
	v_pk_mul_f32 v[18:19], v[2:3], v[18:19]
	v_pk_mul_f32 v[20:21], v[4:5], v[20:21]
	v_pk_mul_f32 v[22:23], v[6:7], v[22:23]
	v_pk_mul_f32 v[24:25], v[8:9], v[24:25]
	s_waitcnt vmcnt(1)
	v_pk_fma_f32 v[2:3], v[14:15], v[34:35], v[42:43]
	v_pk_fma_f32 v[4:5], v[10:11], v[36:37], v[26:27]
	s_waitcnt vmcnt(0)
	v_pk_fma_f32 v[6:7], v[16:17], v[38:39], v[44:45]
	v_pk_fma_f32 v[8:9], v[12:13], v[40:41], v[28:29]
	v_pk_fma_f32 v[10:11], v[34:35], v[18:19], v[46:47]
	v_pk_fma_f32 v[12:13], v[36:37], v[20:21], v[30:31]
	v_pk_fma_f32 v[14:15], v[38:39], v[22:23], v[48:49]
	v_pk_fma_f32 v[16:17], v[40:41], v[24:25], v[32:33]
	global_store_dwordx4 v[64:65], v[2:5], off offset:2048 nt
	global_store_dwordx4 v[64:65], v[6:9], off offset:2064 nt
	global_store_dwordx4 v[62:63], v[10:13], off offset:2048 nt
	global_store_dwordx4 v[62:63], v[14:17], off offset:2064 nt
	s_cbranch_scc1 .LBB0_995
